# v017 + nt on the final-phase f32 output stores (never re-read) + write-through (sc1) x/mem bf16 row stores at the end of the prologue
# speedup vs baseline: 1.0093x; 1.0050x over previous
; #define RESID_LOAD(slot, k) do { const bf16_t* _p = xb + off0 + (size_t)(((k) >> 2) * HALF + ((k) & 3) * 16) * DM; \
;         xv[slot][0] = *(const u32x4*)(_p); xv[slot][1] = *(const u32x4*)(_p + HALF); } while (0)
;     __device__ __forceinline__ void operator()(const f32x4 (&acc)[2][2][4][2], const Unit& u, int wr, int wc, int fr, int fq, float, float, const f32x4&, const f32x4&, float&, float&) const {
;         const int row0 = u.pm * BM + wr * 64 + fr, col0 = u.pn * BM + wc * 32 + 8 * fq;
;         const size_t off0 = (size_t)row0 * DM + col0;
;         u32x4 xv[3][2];
;     ...
;         RESID_LOAD(0, 0); RESID_LOAD(1, 1);
; #pragma unroll
;         for (int k = 0; k < 8; ++k) {
;             const int ai = k >> 2, m = k & 3;
;             if (k + 2 < 8) RESID_LOAD((k + 2) % 3, k + 2);
;             const size_t off = off0 + (size_t)(ai * HALF + m * 16) * DM; float sq = 0.f;
; #pragma unroll
;             for (int bj = 0; bj < 2; ++bj) {
;                 const u32x4 xr = xv[k % 3][bj];
;                 f32x4 x0 = {bf_lo(xr.x), bf_hi(xr.x), bf_lo(xr.y), bf_hi(xr.y)}, x1 = {bf_lo(xr.z), bf_hi(xr.z), bf_lo(xr.w), bf_hi(xr.w)};
;                 x0 = x0 + acc[ai][bj][m][0] * alpha; x1 = x1 + acc[ai][bj][m][1] * alpha;
;                 if (outf) { *(f32x4*)(outf + off + bj * HALF) = x0; *(f32x4*)(outf + off + bj * HALF + 4) = x1; }
.LBB0_207:
	s_lshl_b32 s21, s21, 8
	v_add_u32_e32 v130, s21, v167
	v_lshl_or_b32 v132, s20, 8, v169
	v_ashrrev_i32_e32 v131, 31, v130
	v_lshlrev_b64 v[130:131], 10, v[130:131]
	v_ashrrev_i32_e32 v133, 31, v132
	v_lshl_add_u64 v[162:163], v[130:131], 0, v[132:133]
	v_lshl_add_u64 v[160:161], v[162:163], 1, s[14:15]
	v_add_co_u32_e32 v130, vcc, 0x8000, v160
	s_mov_b32 s10, 0x10000
	s_nop 0
	v_addc_co_u32_e32 v131, vcc, 0, v161, vcc
	global_load_dwordx4 v[176:179], v[160:161], off
	global_load_dwordx4 v[146:149], v[160:161], off offset:256
	global_load_dwordx4 v[142:145], v[130:131], off
	global_load_dwordx4 v[138:141], v[130:131], off offset:256
	v_add_co_u32_e32 v130, vcc, s10, v160
	v_cndmask_b32_e64 v164, 0, 1, s[36:37]
	s_nop 0
	v_addc_co_u32_e32 v131, vcc, 0, v161, vcc
	global_load_dwordx4 v[134:137], v[130:131], off
	s_nop 0
	global_load_dwordx4 v[130:133], v[130:131], off offset:256
	v_cmp_ne_u32_e64 s[10:11], 1, v164
	s_mov_b64 s[12:13], -1
	s_andn2_b64 vcc, exec, s[36:37]
	s_waitcnt vmcnt(0)
	v_lshlrev_b32_e32 v164, 16, v176
	v_and_b32_e32 v165, 0xffff0000, v176
	v_lshlrev_b32_e32 v176, 16, v177
	v_and_b32_e32 v177, 0xffff0000, v177
	v_lshlrev_b32_e32 v192, 16, v178
	v_and_b32_e32 v193, 0xffff0000, v178
	v_lshlrev_b32_e32 v178, 16, v179
	v_and_b32_e32 v179, 0xffff0000, v179
	v_pk_fma_f32 v[124:125], s[30:31], v[124:125], v[176:177]
	v_pk_fma_f32 v[122:123], s[2:3], v[122:123], v[164:165]
	v_pk_fma_f32 v[128:129], s[30:31], v[128:129], v[178:179]
	v_pk_fma_f32 v[126:127], s[2:3], v[126:127], v[192:193]
	v_lshl_add_u64 v[164:165], v[162:163], 2, s[16:17]
	s_cbranch_vccnz .LBB0_209
	s_mov_b64 s[12:13], 0
	global_store_dwordx4 v[164:165], v[122:125], off nt
	global_store_dwordx4 v[164:165], v[126:129], off offset:16 nt

;     __device__ __forceinline__ void operator()(const f32x4 (&acc)[2][2][4][2], const Unit& u, int wr, int wc, int fr, int fq, float, float, const f32x4&, const f32x4&, float&, float&) const {
;     ...
;             const size_t off = off0 + (size_t)(ai * HALF + m * 16) * DM; float sq = 0.f;
; #pragma unroll
;             for (int bj = 0; bj < 2; ++bj) {
;                 const u32x4 xr = xv[k % 3][bj];
;                 f32x4 x0 = {bf_lo(xr.x), bf_hi(xr.x), bf_lo(xr.y), bf_hi(xr.y)}, x1 = {bf_lo(xr.z), bf_hi(xr.z), bf_lo(xr.w), bf_hi(xr.w)};
;                 x0 = x0 + acc[ai][bj][m][0] * alpha; x1 = x1 + acc[ai][bj][m][1] * alpha;
;                 if (outf) { *(f32x4*)(outf + off + bj * HALF) = x0; *(f32x4*)(outf + off + bj * HALF + 4) = x1; }
.LBB0_211:
	v_lshlrev_b32_e32 v122, 16, v146
	v_and_b32_e32 v123, 0xffff0000, v146
	v_lshlrev_b32_e32 v124, 16, v147
	v_and_b32_e32 v125, 0xffff0000, v147
	v_lshlrev_b32_e32 v126, 16, v148
	v_and_b32_e32 v127, 0xffff0000, v148
	v_lshlrev_b32_e32 v128, 16, v149
	v_and_b32_e32 v129, 0xffff0000, v149
	v_pk_fma_f32 v[120:121], s[30:31], v[120:121], v[124:125]
	v_pk_fma_f32 v[118:119], s[2:3], v[118:119], v[122:123]
	v_pk_fma_f32 v[116:117], s[30:31], v[116:117], v[128:129]
	v_pk_fma_f32 v[114:115], s[2:3], v[114:115], v[126:127]
	s_and_b64 vcc, exec, s[10:11]
	s_mov_b64 s[12:13], -1
	s_cbranch_vccnz .LBB0_214
	global_store_dwordx4 v[164:165], v[118:121], off offset:512 nt
	global_store_dwordx4 v[164:165], v[114:117], off offset:528 nt
	s_cbranch_execz .LBB0_215

; #define RESID_LOAD(slot, k) do { const bf16_t* _p = xb + off0 + (size_t)(((k) >> 2) * HALF + ((k) & 3) * 16) * DM; \
;         xv[slot][0] = *(const u32x4*)(_p); xv[slot][1] = *(const u32x4*)(_p + HALF); } while (0)
;     __device__ __forceinline__ void operator()(const f32x4 (&acc)[2][2][4][2], const Unit& u, int wr, int wc, int fr, int fq, float, float, const f32x4&, const f32x4&, float&, float&) const {
;     ...
;         RESID_LOAD(0, 0); RESID_LOAD(1, 1);
; #pragma unroll
;         for (int k = 0; k < 8; ++k) {
;             const int ai = k >> 2, m = k & 3;
;             if (k + 2 < 8) RESID_LOAD((k + 2) % 3, k + 2);
;             const size_t off = off0 + (size_t)(ai * HALF + m * 16) * DM; float sq = 0.f;
; #pragma unroll
;             for (int bj = 0; bj < 2; ++bj) {
;                 const u32x4 xr = xv[k % 3][bj];
;                 f32x4 x0 = {bf_lo(xr.x), bf_hi(xr.x), bf_lo(xr.y), bf_hi(xr.y)}, x1 = {bf_lo(xr.z), bf_hi(xr.z), bf_lo(xr.w), bf_hi(xr.w)};
;                 x0 = x0 + acc[ai][bj][m][0] * alpha; x1 = x1 + acc[ai][bj][m][1] * alpha;
;                 if (outf) { *(f32x4*)(outf + off + bj * HALF) = x0; *(f32x4*)(outf + off + bj * HALF + 4) = x1; }
.LBB0_219:
	v_add_co_u32_e32 v114, vcc, 0x18000, v160
	s_mov_b64 s[40:41], 0x4000
	s_waitcnt lgkmcnt(0)
	v_addc_co_u32_e32 v115, vcc, 0, v161, vcc
	global_load_dwordx4 v[118:121], v[114:115], off
	s_nop 0
	global_load_dwordx4 v[114:117], v[114:115], off offset:256
	v_lshl_add_u64 v[122:123], v[162:163], 0, s[40:41]
	v_lshlrev_b32_e32 v124, 16, v142
	v_and_b32_e32 v125, 0xffff0000, v142
	v_lshlrev_b32_e32 v126, 16, v143
	v_and_b32_e32 v127, 0xffff0000, v143
	v_lshlrev_b32_e32 v128, 16, v144
	v_and_b32_e32 v129, 0xffff0000, v144
	v_lshlrev_b32_e32 v142, 16, v145
	v_and_b32_e32 v143, 0xffff0000, v145
	v_pk_fma_f32 v[112:113], s[30:31], v[112:113], v[126:127]
	v_pk_fma_f32 v[110:111], s[2:3], v[110:111], v[124:125]
	v_pk_fma_f32 v[108:109], s[30:31], v[108:109], v[142:143]
	v_pk_fma_f32 v[106:107], s[2:3], v[106:107], v[128:129]
	s_mov_b64 s[40:41], -1
	s_and_b64 vcc, exec, s[10:11]
	v_lshl_add_u64 v[124:125], v[122:123], 2, s[16:17]
	s_cbranch_vccnz .LBB0_221
	s_mov_b64 s[40:41], 0
	global_store_dwordx4 v[124:125], v[110:113], off nt
	global_store_dwordx4 v[124:125], v[106:109], off offset:16 nt

;     __device__ __forceinline__ void operator()(const f32x4 (&acc)[2][2][4][2], const Unit& u, int wr, int wc, int fr, int fq, float, float, const f32x4&, const f32x4&, float&, float&) const {
;     ...
;                 const u32x4 xr = xv[k % 3][bj];
;                 f32x4 x0 = {bf_lo(xr.x), bf_hi(xr.x), bf_lo(xr.y), bf_hi(xr.y)}, x1 = {bf_lo(xr.z), bf_hi(xr.z), bf_lo(xr.w), bf_hi(xr.w)};
;                 x0 = x0 + acc[ai][bj][m][0] * alpha; x1 = x1 + acc[ai][bj][m][1] * alpha;
;                 if (outf) { *(f32x4*)(outf + off + bj * HALF) = x0; *(f32x4*)(outf + off + bj * HALF + 4) = x1; }
.LBB0_223:
	v_lshlrev_b32_e32 v106, 16, v138
	v_and_b32_e32 v107, 0xffff0000, v138
	v_lshlrev_b32_e32 v108, 16, v139
	v_and_b32_e32 v109, 0xffff0000, v139
	v_lshlrev_b32_e32 v110, 16, v140
	v_and_b32_e32 v111, 0xffff0000, v140
	v_lshlrev_b32_e32 v112, 16, v141
	v_and_b32_e32 v113, 0xffff0000, v141
	v_pk_fma_f32 v[104:105], s[30:31], v[104:105], v[108:109]
	v_pk_fma_f32 v[102:103], s[2:3], v[102:103], v[106:107]
	v_pk_fma_f32 v[100:101], s[30:31], v[100:101], v[112:113]
	v_pk_fma_f32 v[98:99], s[2:3], v[98:99], v[110:111]
	s_and_b64 vcc, exec, s[10:11]
	s_mov_b64 s[40:41], -1
	s_cbranch_vccnz .LBB0_226
	global_store_dwordx4 v[124:125], v[102:105], off offset:512 nt
	global_store_dwordx4 v[124:125], v[98:101], off offset:528 nt
	s_cbranch_execz .LBB0_227

; #define RESID_LOAD(slot, k) do { const bf16_t* _p = xb + off0 + (size_t)(((k) >> 2) * HALF + ((k) & 3) * 16) * DM; \
;         xv[slot][0] = *(const u32x4*)(_p); xv[slot][1] = *(const u32x4*)(_p + HALF); } while (0)
;     __device__ __forceinline__ void operator()(const f32x4 (&acc)[2][2][4][2], const Unit& u, int wr, int wc, int fr, int fq, float, float, const f32x4&, const f32x4&, float&, float&) const {
;     ...
;         RESID_LOAD(0, 0); RESID_LOAD(1, 1);
; #pragma unroll
;         for (int k = 0; k < 8; ++k) {
;             const int ai = k >> 2, m = k & 3;
;             if (k + 2 < 8) RESID_LOAD((k + 2) % 3, k + 2);
;             const size_t off = off0 + (size_t)(ai * HALF + m * 16) * DM; float sq = 0.f;
; #pragma unroll
;             for (int bj = 0; bj < 2; ++bj) {
;                 const u32x4 xr = xv[k % 3][bj];
;                 f32x4 x0 = {bf_lo(xr.x), bf_hi(xr.x), bf_lo(xr.y), bf_hi(xr.y)}, x1 = {bf_lo(xr.z), bf_hi(xr.z), bf_lo(xr.w), bf_hi(xr.w)};
;                 x0 = x0 + acc[ai][bj][m][0] * alpha; x1 = x1 + acc[ai][bj][m][1] * alpha;
;                 if (outf) { *(f32x4*)(outf + off + bj * HALF) = x0; *(f32x4*)(outf + off + bj * HALF + 4) = x1; }
.LBB0_231:
	v_add_co_u32_e32 v98, vcc, 0x40000, v160
	s_mov_b64 s[40:41], 0x8000
	s_waitcnt lgkmcnt(0)
	v_addc_co_u32_e32 v99, vcc, 0, v161, vcc
	global_load_dwordx4 v[102:105], v[98:99], off
	s_nop 0
	global_load_dwordx4 v[98:101], v[98:99], off offset:256
	v_lshl_add_u64 v[106:107], v[162:163], 0, s[40:41]
	v_lshlrev_b32_e32 v108, 16, v134
	v_and_b32_e32 v109, 0xffff0000, v134
	v_lshlrev_b32_e32 v110, 16, v135
	v_and_b32_e32 v111, 0xffff0000, v135
	v_lshlrev_b32_e32 v112, 16, v136
	v_and_b32_e32 v113, 0xffff0000, v136
	v_lshlrev_b32_e32 v122, 16, v137
	v_and_b32_e32 v123, 0xffff0000, v137
	v_pk_fma_f32 v[96:97], s[30:31], v[96:97], v[110:111]
	v_pk_fma_f32 v[94:95], s[2:3], v[94:95], v[108:109]
	v_pk_fma_f32 v[92:93], s[30:31], v[92:93], v[122:123]
	v_pk_fma_f32 v[90:91], s[2:3], v[90:91], v[112:113]
	s_mov_b64 s[40:41], -1
	s_and_b64 vcc, exec, s[10:11]
	v_lshl_add_u64 v[108:109], v[106:107], 2, s[16:17]
	s_cbranch_vccnz .LBB0_233
	s_mov_b64 s[40:41], 0
	global_store_dwordx4 v[108:109], v[94:97], off nt
	global_store_dwordx4 v[108:109], v[90:93], off offset:16 nt

;     __device__ __forceinline__ void operator()(const f32x4 (&acc)[2][2][4][2], const Unit& u, int wr, int wc, int fr, int fq, float, float, const f32x4&, const f32x4&, float&, float&) const {
;     ...
;                 const u32x4 xr = xv[k % 3][bj];
;                 f32x4 x0 = {bf_lo(xr.x), bf_hi(xr.x), bf_lo(xr.y), bf_hi(xr.y)}, x1 = {bf_lo(xr.z), bf_hi(xr.z), bf_lo(xr.w), bf_hi(xr.w)};
;                 x0 = x0 + acc[ai][bj][m][0] * alpha; x1 = x1 + acc[ai][bj][m][1] * alpha;
;                 if (outf) { *(f32x4*)(outf + off + bj * HALF) = x0; *(f32x4*)(outf + off + bj * HALF + 4) = x1; }
.LBB0_235:
	v_lshlrev_b32_e32 v90, 16, v130
	v_and_b32_e32 v91, 0xffff0000, v130
	v_lshlrev_b32_e32 v92, 16, v131
	v_and_b32_e32 v93, 0xffff0000, v131
	v_lshlrev_b32_e32 v94, 16, v132
	v_and_b32_e32 v95, 0xffff0000, v132
	v_lshlrev_b32_e32 v96, 16, v133
	v_and_b32_e32 v97, 0xffff0000, v133
	v_pk_fma_f32 v[88:89], s[30:31], v[88:89], v[92:93]
	v_pk_fma_f32 v[86:87], s[2:3], v[86:87], v[90:91]
	v_pk_fma_f32 v[84:85], s[30:31], v[84:85], v[96:97]
	v_pk_fma_f32 v[82:83], s[2:3], v[82:83], v[94:95]
	s_and_b64 vcc, exec, s[10:11]
	s_mov_b64 s[40:41], -1
	s_cbranch_vccnz .LBB0_238
	global_store_dwordx4 v[108:109], v[86:89], off offset:512 nt
	global_store_dwordx4 v[108:109], v[82:85], off offset:528 nt
	s_cbranch_execz .LBB0_239

; #define RESID_LOAD(slot, k) do { const bf16_t* _p = xb + off0 + (size_t)(((k) >> 2) * HALF + ((k) & 3) * 16) * DM; \
;         xv[slot][0] = *(const u32x4*)(_p); xv[slot][1] = *(const u32x4*)(_p + HALF); } while (0)
;     __device__ __forceinline__ void operator()(const f32x4 (&acc)[2][2][4][2], const Unit& u, int wr, int wc, int fr, int fq, float, float, const f32x4&, const f32x4&, float&, float&) const {
;     ...
;         RESID_LOAD(0, 0); RESID_LOAD(1, 1);
; #pragma unroll
;         for (int k = 0; k < 8; ++k) {
;             const int ai = k >> 2, m = k & 3;
;             if (k + 2 < 8) RESID_LOAD((k + 2) % 3, k + 2);
;             const size_t off = off0 + (size_t)(ai * HALF + m * 16) * DM; float sq = 0.f;
; #pragma unroll
;             for (int bj = 0; bj < 2; ++bj) {
;                 const u32x4 xr = xv[k % 3][bj];
;                 f32x4 x0 = {bf_lo(xr.x), bf_hi(xr.x), bf_lo(xr.y), bf_hi(xr.y)}, x1 = {bf_lo(xr.z), bf_hi(xr.z), bf_lo(xr.w), bf_hi(xr.w)};
;                 x0 = x0 + acc[ai][bj][m][0] * alpha; x1 = x1 + acc[ai][bj][m][1] * alpha;
;                 if (outf) { *(f32x4*)(outf + off + bj * HALF) = x0; *(f32x4*)(outf + off + bj * HALF + 4) = x1; }
.LBB0_243:
	v_add_co_u32_e32 v82, vcc, 0x48000, v160
	s_mov_b64 s[40:41], 0xc000
	s_waitcnt lgkmcnt(0)
	v_addc_co_u32_e32 v83, vcc, 0, v161, vcc
	global_load_dwordx4 v[86:89], v[82:83], off
	s_nop 0
	global_load_dwordx4 v[82:85], v[82:83], off offset:256
	v_lshl_add_u64 v[90:91], v[162:163], 0, s[40:41]
	s_waitcnt vmcnt(5)
	v_lshlrev_b32_e32 v92, 16, v118
	v_and_b32_e32 v93, 0xffff0000, v118
	v_lshlrev_b32_e32 v94, 16, v119
	v_and_b32_e32 v95, 0xffff0000, v119
	v_lshlrev_b32_e32 v96, 16, v120
	v_and_b32_e32 v97, 0xffff0000, v120
	v_lshlrev_b32_e32 v106, 16, v121
	v_and_b32_e32 v107, 0xffff0000, v121
	v_pk_fma_f32 v[80:81], s[30:31], v[80:81], v[94:95]
	v_pk_fma_f32 v[78:79], s[2:3], v[78:79], v[92:93]
	v_pk_fma_f32 v[76:77], s[30:31], v[76:77], v[106:107]
	v_pk_fma_f32 v[74:75], s[2:3], v[74:75], v[96:97]
	s_mov_b64 s[40:41], -1
	s_and_b64 vcc, exec, s[10:11]
	v_lshl_add_u64 v[92:93], v[90:91], 2, s[16:17]
	s_cbranch_vccnz .LBB0_245
	s_mov_b64 s[40:41], 0
	global_store_dwordx4 v[92:93], v[78:81], off nt
	global_store_dwordx4 v[92:93], v[74:77], off offset:16 nt

;     __device__ __forceinline__ void operator()(const f32x4 (&acc)[2][2][4][2], const Unit& u, int wr, int wc, int fr, int fq, float, float, const f32x4&, const f32x4&, float&, float&) const {
;     ...
;                 const u32x4 xr = xv[k % 3][bj];
;                 f32x4 x0 = {bf_lo(xr.x), bf_hi(xr.x), bf_lo(xr.y), bf_hi(xr.y)}, x1 = {bf_lo(xr.z), bf_hi(xr.z), bf_lo(xr.w), bf_hi(xr.w)};
;                 x0 = x0 + acc[ai][bj][m][0] * alpha; x1 = x1 + acc[ai][bj][m][1] * alpha;
;                 if (outf) { *(f32x4*)(outf + off + bj * HALF) = x0; *(f32x4*)(outf + off + bj * HALF + 4) = x1; }
.LBB0_247:
	s_waitcnt vmcnt(4)
	v_lshlrev_b32_e32 v74, 16, v114
	v_and_b32_e32 v75, 0xffff0000, v114
	v_lshlrev_b32_e32 v76, 16, v115
	v_and_b32_e32 v77, 0xffff0000, v115
	v_lshlrev_b32_e32 v78, 16, v116
	v_and_b32_e32 v79, 0xffff0000, v116
	v_lshlrev_b32_e32 v80, 16, v117
	v_and_b32_e32 v81, 0xffff0000, v117
	v_pk_fma_f32 v[72:73], s[30:31], v[72:73], v[76:77]
	v_pk_fma_f32 v[70:71], s[2:3], v[70:71], v[74:75]
	v_pk_fma_f32 v[68:69], s[30:31], v[68:69], v[80:81]
	v_pk_fma_f32 v[66:67], s[2:3], v[66:67], v[78:79]
	s_and_b64 vcc, exec, s[10:11]
	s_mov_b64 s[40:41], -1
	s_cbranch_vccnz .LBB0_250
	global_store_dwordx4 v[92:93], v[70:73], off offset:512 nt
	global_store_dwordx4 v[92:93], v[66:69], off offset:528 nt
	s_cbranch_execz .LBB0_251

; #define RESID_LOAD(slot, k) do { const bf16_t* _p = xb + off0 + (size_t)(((k) >> 2) * HALF + ((k) & 3) * 16) * DM; \
;         xv[slot][0] = *(const u32x4*)(_p); xv[slot][1] = *(const u32x4*)(_p + HALF); } while (0)
;     __device__ __forceinline__ void operator()(const f32x4 (&acc)[2][2][4][2], const Unit& u, int wr, int wc, int fr, int fq, float, float, const f32x4&, const f32x4&, float&, float&) const {
;     ...
;         RESID_LOAD(0, 0); RESID_LOAD(1, 1);
; #pragma unroll
;         for (int k = 0; k < 8; ++k) {
;             const int ai = k >> 2, m = k & 3;
;             if (k + 2 < 8) RESID_LOAD((k + 2) % 3, k + 2);
;             const size_t off = off0 + (size_t)(ai * HALF + m * 16) * DM; float sq = 0.f;
; #pragma unroll
;             for (int bj = 0; bj < 2; ++bj) {
;                 const u32x4 xr = xv[k % 3][bj];
;                 f32x4 x0 = {bf_lo(xr.x), bf_hi(xr.x), bf_lo(xr.y), bf_hi(xr.y)}, x1 = {bf_lo(xr.z), bf_hi(xr.z), bf_lo(xr.w), bf_hi(xr.w)};
;                 x0 = x0 + acc[ai][bj][m][0] * alpha; x1 = x1 + acc[ai][bj][m][1] * alpha;
;                 if (outf) { *(f32x4*)(outf + off + bj * HALF) = x0; *(f32x4*)(outf + off + bj * HALF + 4) = x1; }
.LBB0_255:
	v_add_co_u32_e32 v66, vcc, 0x50000, v160
	v_lshl_add_u64 v[74:75], v[162:163], 0, s[68:69]
	s_waitcnt lgkmcnt(0)
	v_addc_co_u32_e32 v67, vcc, 0, v161, vcc
	global_load_dwordx4 v[70:73], v[66:67], off
	s_nop 0
	global_load_dwordx4 v[66:69], v[66:67], off offset:256
	s_waitcnt vmcnt(5)
	v_lshlrev_b32_e32 v76, 16, v102
	v_and_b32_e32 v77, 0xffff0000, v102
	v_lshlrev_b32_e32 v78, 16, v103
	v_and_b32_e32 v79, 0xffff0000, v103
	v_lshlrev_b32_e32 v80, 16, v104
	v_and_b32_e32 v81, 0xffff0000, v104
	v_lshlrev_b32_e32 v90, 16, v105
	v_and_b32_e32 v91, 0xffff0000, v105
	v_pk_fma_f32 v[64:65], s[30:31], v[64:65], v[78:79]
	v_pk_fma_f32 v[62:63], s[2:3], v[62:63], v[76:77]
	v_pk_fma_f32 v[60:61], s[30:31], v[60:61], v[90:91]
	v_pk_fma_f32 v[58:59], s[2:3], v[58:59], v[80:81]
	s_mov_b64 s[40:41], -1
	s_and_b64 vcc, exec, s[10:11]
	v_lshl_add_u64 v[76:77], v[74:75], 2, s[16:17]
	s_cbranch_vccnz .LBB0_257
	s_mov_b64 s[40:41], 0
	global_store_dwordx4 v[76:77], v[62:65], off nt
	global_store_dwordx4 v[76:77], v[58:61], off offset:16 nt

;     __device__ __forceinline__ void operator()(const f32x4 (&acc)[2][2][4][2], const Unit& u, int wr, int wc, int fr, int fq, float, float, const f32x4&, const f32x4&, float&, float&) const {
;     ...
;                 const u32x4 xr = xv[k % 3][bj];
;                 f32x4 x0 = {bf_lo(xr.x), bf_hi(xr.x), bf_lo(xr.y), bf_hi(xr.y)}, x1 = {bf_lo(xr.z), bf_hi(xr.z), bf_lo(xr.w), bf_hi(xr.w)};
;                 x0 = x0 + acc[ai][bj][m][0] * alpha; x1 = x1 + acc[ai][bj][m][1] * alpha;
;                 if (outf) { *(f32x4*)(outf + off + bj * HALF) = x0; *(f32x4*)(outf + off + bj * HALF + 4) = x1; }
.LBB0_259:
	s_waitcnt vmcnt(4)
	v_lshlrev_b32_e32 v58, 16, v98
	v_and_b32_e32 v59, 0xffff0000, v98
	v_lshlrev_b32_e32 v60, 16, v99
	v_and_b32_e32 v61, 0xffff0000, v99
	v_lshlrev_b32_e32 v62, 16, v100
	v_and_b32_e32 v63, 0xffff0000, v100
	v_lshlrev_b32_e32 v64, 16, v101
	v_and_b32_e32 v65, 0xffff0000, v101
	v_pk_fma_f32 v[56:57], s[30:31], v[56:57], v[60:61]
	v_pk_fma_f32 v[54:55], s[2:3], v[54:55], v[58:59]
	v_pk_fma_f32 v[52:53], s[30:31], v[52:53], v[64:65]
	v_pk_fma_f32 v[50:51], s[2:3], v[50:51], v[62:63]
	s_and_b64 vcc, exec, s[10:11]
	s_mov_b64 s[40:41], -1
	s_cbranch_vccnz .LBB0_262
	global_store_dwordx4 v[76:77], v[54:57], off offset:512 nt
	global_store_dwordx4 v[76:77], v[50:53], off offset:528 nt
	s_cbranch_execz .LBB0_263

; #define RESID_LOAD(slot, k) do { const bf16_t* _p = xb + off0 + (size_t)(((k) >> 2) * HALF + ((k) & 3) * 16) * DM; \
;         xv[slot][0] = *(const u32x4*)(_p); xv[slot][1] = *(const u32x4*)(_p + HALF); } while (0)
;     __device__ __forceinline__ void operator()(const f32x4 (&acc)[2][2][4][2], const Unit& u, int wr, int wc, int fr, int fq, float, float, const f32x4&, const f32x4&, float&, float&) const {
;     ...
;         RESID_LOAD(0, 0); RESID_LOAD(1, 1);
; #pragma unroll
;         for (int k = 0; k < 8; ++k) {
;             const int ai = k >> 2, m = k & 3;
;             if (k + 2 < 8) RESID_LOAD((k + 2) % 3, k + 2);
;             const size_t off = off0 + (size_t)(ai * HALF + m * 16) * DM; float sq = 0.f;
; #pragma unroll
;             for (int bj = 0; bj < 2; ++bj) {
;                 const u32x4 xr = xv[k % 3][bj];
;                 f32x4 x0 = {bf_lo(xr.x), bf_hi(xr.x), bf_lo(xr.y), bf_hi(xr.y)}, x1 = {bf_lo(xr.z), bf_hi(xr.z), bf_lo(xr.w), bf_hi(xr.w)};
;                 x0 = x0 + acc[ai][bj][m][0] * alpha; x1 = x1 + acc[ai][bj][m][1] * alpha;
;                 if (outf) { *(f32x4*)(outf + off + bj * HALF) = x0; *(f32x4*)(outf + off + bj * HALF + 4) = x1; }
.LBB0_267:
	v_add_co_u32_e32 v50, vcc, 0x58000, v160
	s_mov_b64 s[40:41], 0x24000
	s_waitcnt lgkmcnt(0)
	v_addc_co_u32_e32 v51, vcc, 0, v161, vcc
	global_load_dwordx4 v[54:57], v[50:51], off
	s_nop 0
	global_load_dwordx4 v[50:53], v[50:51], off offset:256
	v_lshl_add_u64 v[58:59], v[162:163], 0, s[40:41]
	s_waitcnt vmcnt(5)
	v_lshlrev_b32_e32 v60, 16, v86
	v_and_b32_e32 v61, 0xffff0000, v86
	v_lshlrev_b32_e32 v62, 16, v87
	v_and_b32_e32 v63, 0xffff0000, v87
	v_lshlrev_b32_e32 v64, 16, v88
	v_and_b32_e32 v65, 0xffff0000, v88
	v_lshlrev_b32_e32 v74, 16, v89
	v_and_b32_e32 v75, 0xffff0000, v89
	v_pk_fma_f32 v[48:49], s[30:31], v[48:49], v[62:63]
	v_pk_fma_f32 v[46:47], s[2:3], v[46:47], v[60:61]
	v_pk_fma_f32 v[44:45], s[30:31], v[44:45], v[74:75]
	v_pk_fma_f32 v[42:43], s[2:3], v[42:43], v[64:65]
	s_mov_b64 s[40:41], -1
	s_and_b64 vcc, exec, s[10:11]
	v_lshl_add_u64 v[60:61], v[58:59], 2, s[16:17]
	s_cbranch_vccnz .LBB0_269
	s_mov_b64 s[40:41], 0
	global_store_dwordx4 v[60:61], v[46:49], off nt
	global_store_dwordx4 v[60:61], v[42:45], off offset:16 nt

;     __device__ __forceinline__ void operator()(const f32x4 (&acc)[2][2][4][2], const Unit& u, int wr, int wc, int fr, int fq, float, float, const f32x4&, const f32x4&, float&, float&) const {
;     ...
;                 const u32x4 xr = xv[k % 3][bj];
;                 f32x4 x0 = {bf_lo(xr.x), bf_hi(xr.x), bf_lo(xr.y), bf_hi(xr.y)}, x1 = {bf_lo(xr.z), bf_hi(xr.z), bf_lo(xr.w), bf_hi(xr.w)};
;                 x0 = x0 + acc[ai][bj][m][0] * alpha; x1 = x1 + acc[ai][bj][m][1] * alpha;
;                 if (outf) { *(f32x4*)(outf + off + bj * HALF) = x0; *(f32x4*)(outf + off + bj * HALF + 4) = x1; }
.LBB0_271:
	s_waitcnt vmcnt(4)
	v_lshlrev_b32_e32 v42, 16, v82
	v_and_b32_e32 v43, 0xffff0000, v82
	v_lshlrev_b32_e32 v44, 16, v83
	v_and_b32_e32 v45, 0xffff0000, v83
	v_lshlrev_b32_e32 v46, 16, v84
	v_and_b32_e32 v47, 0xffff0000, v84
	v_lshlrev_b32_e32 v48, 16, v85
	v_and_b32_e32 v49, 0xffff0000, v85
	v_pk_fma_f32 v[40:41], s[30:31], v[40:41], v[44:45]
	v_pk_fma_f32 v[38:39], s[2:3], v[38:39], v[42:43]
	v_pk_fma_f32 v[36:37], s[30:31], v[36:37], v[48:49]
	v_pk_fma_f32 v[34:35], s[2:3], v[34:35], v[46:47]
	s_and_b64 vcc, exec, s[10:11]
	s_mov_b64 s[40:41], -1
	s_cbranch_vccnz .LBB0_274
	global_store_dwordx4 v[60:61], v[38:41], off offset:512 nt
	global_store_dwordx4 v[60:61], v[34:37], off offset:528 nt
	s_cbranch_execz .LBB0_275

;     __device__ __forceinline__ void operator()(const f32x4 (&acc)[2][2][4][2], const Unit& u, int wr, int wc, int fr, int fq, float, float, const f32x4&, const f32x4&, float&, float&) const {
;     ...
;             const size_t off = off0 + (size_t)(ai * HALF + m * 16) * DM; float sq = 0.f;
; #pragma unroll
;             for (int bj = 0; bj < 2; ++bj) {
;                 const u32x4 xr = xv[k % 3][bj];
;                 f32x4 x0 = {bf_lo(xr.x), bf_hi(xr.x), bf_lo(xr.y), bf_hi(xr.y)}, x1 = {bf_lo(xr.z), bf_hi(xr.z), bf_lo(xr.w), bf_hi(xr.w)};
;                 x0 = x0 + acc[ai][bj][m][0] * alpha; x1 = x1 + acc[ai][bj][m][1] * alpha;
;                 if (outf) { *(f32x4*)(outf + off + bj * HALF) = x0; *(f32x4*)(outf + off + bj * HALF + 4) = x1; }
.LBB0_279:
	s_mov_b64 s[40:41], 0x28000
	s_waitcnt lgkmcnt(0)
	v_lshl_add_u64 v[34:35], v[162:163], 0, s[40:41]
	s_waitcnt vmcnt(3)
	v_lshlrev_b32_e32 v36, 16, v70
	v_and_b32_e32 v37, 0xffff0000, v70
	v_lshlrev_b32_e32 v38, 16, v71
	v_and_b32_e32 v39, 0xffff0000, v71
	v_lshlrev_b32_e32 v40, 16, v72
	v_and_b32_e32 v41, 0xffff0000, v72
	v_lshlrev_b32_e32 v42, 16, v73
	v_and_b32_e32 v43, 0xffff0000, v73
	v_pk_fma_f32 v[32:33], s[30:31], v[32:33], v[38:39]
	v_pk_fma_f32 v[30:31], s[2:3], v[30:31], v[36:37]
	v_pk_fma_f32 v[28:29], s[30:31], v[28:29], v[42:43]
	v_pk_fma_f32 v[26:27], s[2:3], v[26:27], v[40:41]
	s_mov_b64 s[40:41], -1
	s_and_b64 vcc, exec, s[10:11]
	v_lshl_add_u64 v[36:37], v[34:35], 2, s[16:17]
	s_cbranch_vccnz .LBB0_281
	s_mov_b64 s[40:41], 0
	global_store_dwordx4 v[36:37], v[30:33], off nt
	global_store_dwordx4 v[36:37], v[26:29], off offset:16 nt

;     __device__ __forceinline__ void operator()(const f32x4 (&acc)[2][2][4][2], const Unit& u, int wr, int wc, int fr, int fq, float, float, const f32x4&, const f32x4&, float&, float&) const {
;     ...
;                 const u32x4 xr = xv[k % 3][bj];
;                 f32x4 x0 = {bf_lo(xr.x), bf_hi(xr.x), bf_lo(xr.y), bf_hi(xr.y)}, x1 = {bf_lo(xr.z), bf_hi(xr.z), bf_lo(xr.w), bf_hi(xr.w)};
;                 x0 = x0 + acc[ai][bj][m][0] * alpha; x1 = x1 + acc[ai][bj][m][1] * alpha;
;                 if (outf) { *(f32x4*)(outf + off + bj * HALF) = x0; *(f32x4*)(outf + off + bj * HALF + 4) = x1; }
.LBB0_283:
	s_waitcnt vmcnt(2)
	v_lshlrev_b32_e32 v26, 16, v66
	v_and_b32_e32 v27, 0xffff0000, v66
	v_lshlrev_b32_e32 v28, 16, v67
	v_and_b32_e32 v29, 0xffff0000, v67
	v_lshlrev_b32_e32 v30, 16, v68
	v_and_b32_e32 v31, 0xffff0000, v68
	v_lshlrev_b32_e32 v32, 16, v69
	v_and_b32_e32 v33, 0xffff0000, v69
	v_pk_fma_f32 v[24:25], s[30:31], v[24:25], v[28:29]
	v_pk_fma_f32 v[22:23], s[2:3], v[22:23], v[26:27]
	v_pk_fma_f32 v[20:21], s[30:31], v[20:21], v[32:33]
	v_pk_fma_f32 v[18:19], s[2:3], v[18:19], v[30:31]
	s_and_b64 vcc, exec, s[10:11]
	s_mov_b64 s[40:41], -1
	s_cbranch_vccnz .LBB0_286
	global_store_dwordx4 v[36:37], v[22:25], off offset:512 nt
	global_store_dwordx4 v[36:37], v[18:21], off offset:528 nt
	s_cbranch_execz .LBB0_287

;     __device__ __forceinline__ void operator()(const f32x4 (&acc)[2][2][4][2], const Unit& u, int wr, int wc, int fr, int fq, float, float, const f32x4&, const f32x4&, float&, float&) const {
;     ...
;             const size_t off = off0 + (size_t)(ai * HALF + m * 16) * DM; float sq = 0.f;
; #pragma unroll
;             for (int bj = 0; bj < 2; ++bj) {
;                 const u32x4 xr = xv[k % 3][bj];
;                 f32x4 x0 = {bf_lo(xr.x), bf_hi(xr.x), bf_lo(xr.y), bf_hi(xr.y)}, x1 = {bf_lo(xr.z), bf_hi(xr.z), bf_lo(xr.w), bf_hi(xr.w)};
;                 x0 = x0 + acc[ai][bj][m][0] * alpha; x1 = x1 + acc[ai][bj][m][1] * alpha;
;                 if (outf) { *(f32x4*)(outf + off + bj * HALF) = x0; *(f32x4*)(outf + off + bj * HALF + 4) = x1; }
.LBB0_291:
	s_mov_b64 s[40:41], 0x2c000
	s_waitcnt lgkmcnt(0)
	v_lshl_add_u64 v[18:19], v[162:163], 0, s[40:41]
	s_waitcnt vmcnt(1)
	v_lshlrev_b32_e32 v20, 16, v54
	v_and_b32_e32 v21, 0xffff0000, v54
	v_lshlrev_b32_e32 v22, 16, v55
	v_and_b32_e32 v23, 0xffff0000, v55
	v_lshlrev_b32_e32 v24, 16, v56
	v_and_b32_e32 v25, 0xffff0000, v56
	v_lshlrev_b32_e32 v26, 16, v57
	v_and_b32_e32 v27, 0xffff0000, v57
	v_pk_fma_f32 v[16:17], s[30:31], v[16:17], v[22:23]
	v_pk_fma_f32 v[14:15], s[2:3], v[14:15], v[20:21]
	v_pk_fma_f32 v[12:13], s[30:31], v[12:13], v[26:27]
	v_pk_fma_f32 v[10:11], s[2:3], v[10:11], v[24:25]
	s_mov_b64 s[40:41], -1
	s_and_b64 vcc, exec, s[10:11]
	v_lshl_add_u64 v[20:21], v[18:19], 2, s[16:17]
	s_cbranch_vccnz .LBB0_293
	s_mov_b64 s[40:41], 0
	global_store_dwordx4 v[20:21], v[14:17], off nt
	global_store_dwordx4 v[20:21], v[10:13], off offset:16 nt

;     __device__ __forceinline__ void operator()(const f32x4 (&acc)[2][2][4][2], const Unit& u, int wr, int wc, int fr, int fq, float, float, const f32x4&, const f32x4&, float&, float&) const {
;     ...
;                 const u32x4 xr = xv[k % 3][bj];
;                 f32x4 x0 = {bf_lo(xr.x), bf_hi(xr.x), bf_lo(xr.y), bf_hi(xr.y)}, x1 = {bf_lo(xr.z), bf_hi(xr.z), bf_lo(xr.w), bf_hi(xr.w)};
;                 x0 = x0 + acc[ai][bj][m][0] * alpha; x1 = x1 + acc[ai][bj][m][1] * alpha;
;                 if (outf) { *(f32x4*)(outf + off + bj * HALF) = x0; *(f32x4*)(outf + off + bj * HALF + 4) = x1; }
.LBB0_295:
	s_waitcnt vmcnt(0)
	v_lshlrev_b32_e32 v10, 16, v50
	v_and_b32_e32 v11, 0xffff0000, v50
	v_lshlrev_b32_e32 v12, 16, v51
	v_and_b32_e32 v13, 0xffff0000, v51
	v_lshlrev_b32_e32 v14, 16, v52
	v_and_b32_e32 v15, 0xffff0000, v52
	v_lshlrev_b32_e32 v16, 16, v53
	v_and_b32_e32 v17, 0xffff0000, v53
	v_pk_fma_f32 v[8:9], s[30:31], v[8:9], v[12:13]
	v_pk_fma_f32 v[6:7], s[2:3], v[6:7], v[10:11]
	v_pk_fma_f32 v[4:5], s[30:31], v[4:5], v[16:17]
	v_pk_fma_f32 v[2:3], s[2:3], v[2:3], v[14:15]
	s_and_b64 vcc, exec, s[10:11]
	s_mov_b64 s[10:11], -1
	s_cbranch_vccnz .LBB0_299
	global_store_dwordx4 v[20:21], v[6:9], off offset:512 nt
	global_store_dwordx4 v[20:21], v[2:5], off offset:528 nt
	s_cbranch_execz .LBB0_300

; __device__ __forceinline__ unsigned pk_bf16(float lo, float hi) { f32x2 v = {lo, hi}; bf16x2_t b = __builtin_convertvector(v, bf16x2_t); return __builtin_bit_cast(unsigned, b); }
; __device__ __forceinline__ float wave_sum(float v) {
; #pragma unroll
;     for (int o = 1; o < 64; o <<= 1) v += __shfl_xor(v, o);
;     return v;
; __device__ __forceinline__ void prologue(const Params& p, LAS unsigned char* lds, int gw, int NGW, int wave, int lane) {
;     ...
;         f32x4 a[4], b[4];
; #pragma unroll
;         for (int j = 0; j < 4; ++j) { a[j] = x1[64 * j]; b[j] = x2[64 * j]; }
;         float sa = 0.f, sb = 0.f;
; #pragma unroll
;         for (int j = 0; j < 4; ++j) { sa += (a[j].x * a[j].x + a[j].y * a[j].y) + (a[j].z * a[j].z + a[j].w * a[j].w); sb += (b[j].x * b[j].x + b[j].y * b[j].y) + (b[j].z * b[j].z + b[j].w * b[j].w); }
;         sa = wave_sum(sa); sb = wave_sum(sb);
;         u32x2* o1 = (u32x2*)(xb + (size_t)m * DM) + lane;
; #pragma unroll
;         for (int j = 0; j < 4; ++j) { u32x2 w; w.x = pk_bf16(a[j].x, a[j].y); w.y = pk_bf16(a[j].z, a[j].w); o1[64 * j] = w; }
;         if (lane < 4) ssq[(size_t)m * 4 + lane] = lane == 0 ? sa : 0.f;
.LBB0_385:
	global_load_dwordx4 v[28:31], v0, s[14:15] nt
	global_load_dwordx4 v[14:17], v0, s[16:17] nt
	global_load_dwordx4 v[32:35], v0, s[14:15] offset:1024 nt
	global_load_dwordx4 v[10:13], v0, s[16:17] offset:1024 nt
	global_load_dwordx4 v[36:39], v0, s[14:15] offset:2048 nt
	global_load_dwordx4 v[6:9], v0, s[16:17] offset:2048 nt
	global_load_dwordx4 v[40:43], v0, s[14:15] offset:3072 nt
	global_load_dwordx4 v[2:5], v0, s[16:17] offset:3072 nt
	s_lshl_b64 s[14:15], s[2:3], 11
	s_waitcnt vmcnt(7)
	v_mul_f32_e32 v44, v29, v29
	v_mul_f32_e32 v45, v31, v31
	s_waitcnt vmcnt(6)
	v_mul_f32_e32 v46, v15, v15
	v_mul_f32_e32 v47, v17, v17
	s_waitcnt vmcnt(5)
	v_mul_f32_e32 v48, v33, v33
	v_mul_f32_e32 v49, v35, v35
	s_waitcnt vmcnt(4)
	v_mul_f32_e32 v50, v11, v11
	v_mul_f32_e32 v51, v13, v13
	s_waitcnt vmcnt(3)
	v_mul_f32_e32 v52, v37, v37
	v_mul_f32_e32 v53, v39, v39
	s_waitcnt vmcnt(2)
	v_mul_f32_e32 v54, v7, v7
	v_mul_f32_e32 v55, v9, v9
	v_fmac_f32_e32 v44, v28, v28
	v_fmac_f32_e32 v45, v30, v30
	v_fmac_f32_e32 v46, v14, v14
	v_fmac_f32_e32 v47, v16, v16
	v_fmac_f32_e32 v48, v32, v32
	v_fmac_f32_e32 v49, v34, v34
	v_fmac_f32_e32 v50, v10, v10
	v_fmac_f32_e32 v51, v12, v12
	s_waitcnt vmcnt(1)
	v_mul_f32_e32 v56, v41, v41
	v_mul_f32_e32 v57, v43, v43
	s_waitcnt vmcnt(0)
	v_mul_f32_e32 v58, v3, v3
	v_mul_f32_e32 v59, v5, v5
	v_fmac_f32_e32 v52, v36, v36
	v_fmac_f32_e32 v53, v38, v38
	v_fmac_f32_e32 v54, v6, v6
	v_fmac_f32_e32 v55, v8, v8
	v_add_f32_e32 v44, v44, v45
	v_add_f32_e32 v45, v46, v47
	v_add_f32_e32 v46, v48, v49
	v_add_f32_e32 v47, v50, v51
	v_fmac_f32_e32 v56, v40, v40
	v_fmac_f32_e32 v57, v42, v42
	v_fmac_f32_e32 v58, v2, v2
	v_fmac_f32_e32 v59, v4, v4
	v_add_f32_e32 v48, v52, v53
	v_add_f32_e32 v49, v54, v55
	v_add_f32_e32 v44, v44, v46
	v_add_f32_e32 v45, v45, v47
	v_add_f32_e32 v50, v56, v57
	v_add_f32_e32 v51, v58, v59
	v_add_f32_e32 v44, v44, v48
	v_add_f32_e32 v45, v45, v49
	v_add_f32_e32 v44, v44, v50
	v_add_f32_e32 v45, v45, v51
	ds_bpermute_b32 v46, v22, v44
	ds_bpermute_b32 v47, v22, v45
	v_cvt_pk_bf16_f32 v28, v28, v29
	v_cvt_pk_bf16_f32 v29, v30, v31
	v_cvt_pk_bf16_f32 v30, v32, v33
	s_waitcnt lgkmcnt(1)
	v_add_f32_e32 v44, v44, v46
	s_waitcnt lgkmcnt(0)
	v_add_f32_e32 v45, v45, v47
	ds_bpermute_b32 v46, v23, v44
	ds_bpermute_b32 v47, v23, v45
	v_cvt_pk_bf16_f32 v31, v34, v35
	v_cvt_pk_bf16_f32 v32, v36, v37
	s_waitcnt lgkmcnt(1)
	v_add_f32_e32 v46, v44, v46
	s_waitcnt lgkmcnt(0)
	v_add_f32_e32 v47, v45, v47
	ds_bpermute_b32 v48, v24, v46
	ds_bpermute_b32 v49, v24, v47
	v_lshl_add_u64 v[44:45], v[18:19], 0, s[14:15]
	global_store_dwordx2 v[44:45], v[28:29], off sc1
	global_store_dwordx2 v[44:45], v[30:31], off offset:512 sc1
	s_waitcnt lgkmcnt(1)
	v_add_f32_e32 v46, v46, v48
	s_waitcnt lgkmcnt(0)
	v_add_f32_e32 v47, v47, v49
	ds_bpermute_b32 v48, v25, v46
	ds_bpermute_b32 v49, v25, v47
	s_waitcnt lgkmcnt(1)
	v_add_f32_e32 v33, v46, v48
	s_waitcnt lgkmcnt(0)
	v_add_f32_e32 v34, v47, v49
	ds_bpermute_b32 v35, v26, v33
	ds_bpermute_b32 v46, v26, v34
	s_waitcnt lgkmcnt(1)
	v_add_f32_e32 v30, v33, v35
	s_waitcnt lgkmcnt(0)
	v_add_f32_e32 v28, v34, v46
	ds_bpermute_b32 v31, v27, v30
	ds_bpermute_b32 v29, v27, v28
	v_cvt_pk_bf16_f32 v33, v38, v39
	global_store_dwordx2 v[44:45], v[32:33], off offset:1024 sc1
	v_cvt_pk_bf16_f32 v32, v40, v41
	v_cvt_pk_bf16_f32 v33, v42, v43
	global_store_dwordx2 v[44:45], v[32:33], off offset:1536 sc1
	s_and_saveexec_b64 s[14:15], s[4:5]
	s_cbranch_execz .LBB0_387
	s_waitcnt lgkmcnt(1)
	v_add_f32_e32 v30, v30, v31
	v_cndmask_b32_e64 v32, 0, v30, s[6:7]
	v_lshl_add_u64 v[30:31], s[2:3], 4, v[20:21]
	global_store_dword v[30:31], v32, off
	s_or_b64 exec, exec, s[14:15]
	s_andn2_b64 vcc, exec, s[12:13]
	s_cbranch_vccnz .LBB0_379
	s_branch .LBB0_388

; __device__ __forceinline__ unsigned pk_bf16(float lo, float hi) { f32x2 v = {lo, hi}; bf16x2_t b = __builtin_convertvector(v, bf16x2_t); return __builtin_bit_cast(unsigned, b); }
; __device__ __forceinline__ void prologue(const Params& p, LAS unsigned char* lds, int gw, int NGW, int wave, int lane) {
;     ...
;         if (two) {
;             u32x2* o2 = (u32x2*)(xb + (size_t)m2 * DM) + lane;
; #pragma unroll
;             for (int j = 0; j < 4; ++j) { u32x2 w; w.x = pk_bf16(b[j].x, b[j].y); w.y = pk_bf16(b[j].z, b[j].w); o2[64 * j] = w; }
;             if (lane < 4) ssq[(size_t)m2 * 4 + lane] = lane == 0 ? sb : 0.f;
.LBB0_388:
	s_ashr_i32 s1, s0, 31
	s_lshl_b64 s[2:3], s[0:1], 11
	s_waitcnt lgkmcnt(1)
	v_lshl_add_u64 v[30:31], v[18:19], 0, s[2:3]
	v_cvt_pk_bf16_f32 v14, v14, v15
	v_cvt_pk_bf16_f32 v15, v16, v17
	v_cvt_pk_bf16_f32 v10, v10, v11
	v_cvt_pk_bf16_f32 v11, v12, v13
	v_cvt_pk_bf16_f32 v6, v6, v7
	v_cvt_pk_bf16_f32 v7, v8, v9
	v_cvt_pk_bf16_f32 v2, v2, v3
	v_cvt_pk_bf16_f32 v3, v4, v5
	global_store_dwordx2 v[30:31], v[14:15], off sc1
	global_store_dwordx2 v[30:31], v[10:11], off offset:512 sc1
	global_store_dwordx2 v[30:31], v[6:7], off offset:1024 sc1
	global_store_dwordx2 v[30:31], v[2:3], off offset:1536 sc1
	s_and_saveexec_b64 s[2:3], s[4:5]
	s_cbranch_execz .LBB0_378
	s_waitcnt lgkmcnt(0)
	v_add_f32_e32 v2, v28, v29
	v_cndmask_b32_e64 v4, 0, v2, s[6:7]
	v_lshl_add_u64 v[2:3], s[0:1], 4, v[20:21]
	global_store_dword v[2:3], v4, off
	s_branch .LBB0_378
